# nt stores for P (scores epilogue), two-chain row-max in attention softmax
# baseline (speedup 1.0000x reference)
.LBB0_750:
	s_nop 1
	v_max3_f32 v65, v32, v33, v34
	v_max3_f32 v66, v48, v49, v50
	v_max3_f32 v65, v65, v35, v36
	v_max3_f32 v66, v66, v51, v52
	v_max3_f32 v65, v65, v37, v38
	v_max3_f32 v66, v66, v53, v54
	v_max3_f32 v65, v65, v39, v40
	v_max3_f32 v66, v66, v55, v56
	v_max3_f32 v65, v65, v41, v42
	v_max3_f32 v66, v66, v57, v58
	v_max3_f32 v65, v65, v43, v44
	v_max3_f32 v66, v66, v59, v60
	v_max3_f32 v65, v65, v45, v46
	v_max3_f32 v66, v66, v61, v62
	v_max3_f32 v65, v65, v66, v47
	v_max_f32_e32 v65, v65, v63
	v_mov_b32_e32 v66, v65
	s_nop 1
	v_permlane32_swap_b32_e32 v65, v66
	s_cmp_lg_u32 s49, 63
	v_max_f32_e32 v66, v65, v66
	s_cselect_b64 s[2:3], -1, 0
	s_cmp_eq_u32 s49, 63
	s_mov_b64 s[28:29], -1
	s_cbranch_scc1 .LBB0_753
	v_cmp_lt_f32_e32 vcc, 0x41000000, v66
	s_cbranch_vccz .LBB0_758
	v_max_f32_e32 v65, v66, v66
	v_max_f32_e32 v66, 0, v65

.LBB0_1751:
	s_or_b64 exec, exec, s[0:1]
	s_add_i32 s0, 0, 0x21000
	s_waitcnt lgkmcnt(0)
	s_barrier
	v_add_u32_e32 v134, s0, v208
	ds_read_b128 v[138:141], v134
	v_lshl_or_b32 v16, s48, 8, v207
	s_waitcnt lgkmcnt(0)
	v_ashrrev_i32_e32 v17, 31, v16
	v_lshlrev_b64 v[132:133], 11, v[132:133]
	v_lshl_add_u64 v[132:133], s[18:19], 0, v[132:133]
	v_mov_b32_e32 v134, v139
	v_mov_b32_e32 v135, v140
	v_mov_b32_e32 v139, v141
	v_pk_add_f32 v[134:135], v[134:135], v[138:139]
	v_lshlrev_b64 v[16:17], 1, v[16:17]
	v_add_f32_e32 v134, v134, v135
	v_rcp_f32_e32 v134, v134
	v_lshl_add_u64 v[132:133], v[132:133], 0, v[16:17]
	s_and_b64 vcc, exec, s[8:9]
	v_pk_mul_f32 v[116:117], v[116:117], v[134:135] op_sel_hi:[1,0]
	v_pk_mul_f32 v[114:115], v[114:115], v[134:135] op_sel_hi:[1,0]
	v_pk_mul_f32 v[120:121], v[120:121], v[134:135] op_sel_hi:[1,0]
	v_pk_mul_f32 v[118:119], v[118:119], v[134:135] op_sel_hi:[1,0]
	v_cvt_pk_bf16_f32 v114, v114, v115
	v_cvt_pk_bf16_f32 v115, v116, v117
	v_cvt_pk_bf16_f32 v116, v118, v119
	v_cvt_pk_bf16_f32 v117, v120, v121
	global_store_dwordx4 v[132:133], v[114:117], off nt
	v_pk_mul_f32 v[118:119], v[136:137], v[134:135] op_sel_hi:[1,0]
	v_pk_mul_f32 v[120:121], v[126:127], v[134:135] op_sel_hi:[1,0]
	v_pk_mul_f32 v[116:117], v[124:125], v[134:135] op_sel_hi:[1,0]
	v_pk_mul_f32 v[114:115], v[122:123], v[134:135] op_sel_hi:[1,0]
	s_nop 0
	v_cvt_pk_bf16_f32 v114, v114, v115
	v_cvt_pk_bf16_f32 v115, v116, v117
	v_cvt_pk_bf16_f32 v116, v120, v121
	v_cvt_pk_bf16_f32 v117, v118, v119
	global_store_dwordx4 v[132:133], v[114:117], off offset:256 nt
	s_nop 1
	v_add_u32_e32 v114, s0, v219
	ds_read_b128 v[114:117], v114
	s_waitcnt lgkmcnt(0)
	v_mov_b32_e32 v118, v115
	v_mov_b32_e32 v119, v116
	v_mov_b32_e32 v115, v117
	v_pk_add_f32 v[114:115], v[118:119], v[114:115]
	v_add_u32_e32 v116, s2, v218
	v_add_f32_e32 v114, v114, v115
	v_rcp_f32_e32 v114, v114
	v_ashrrev_i32_e32 v117, 31, v116
	v_lshlrev_b64 v[116:117], 11, v[116:117]
	v_lshl_add_u64 v[116:117], s[18:19], 0, v[116:117]
	v_pk_mul_f32 v[88:89], v[88:89], v[114:115] op_sel_hi:[1,0]
	v_pk_mul_f32 v[82:83], v[82:83], v[114:115] op_sel_hi:[1,0]
	v_pk_mul_f32 v[94:95], v[94:95], v[114:115] op_sel_hi:[1,0]
	v_pk_mul_f32 v[118:119], v[86:87], v[114:115] op_sel_hi:[1,0]
	v_lshl_add_u64 v[116:117], v[116:117], 0, v[16:17]
	v_cvt_pk_bf16_f32 v86, v82, v83
	v_cvt_pk_bf16_f32 v87, v88, v89
	v_cvt_pk_bf16_f32 v88, v118, v119
	v_cvt_pk_bf16_f32 v89, v94, v95
	global_store_dwordx4 v[116:117], v[86:89], off nt
	v_pk_mul_f32 v[82:83], v[84:85], v[114:115] op_sel_hi:[1,0]
	v_pk_mul_f32 v[84:85], v[92:93], v[114:115] op_sel_hi:[1,0]
	v_pk_mul_f32 v[86:87], v[90:91], v[114:115] op_sel_hi:[1,0]
	v_pk_mul_f32 v[88:89], v[100:101], v[114:115] op_sel_hi:[1,0]
	v_cvt_pk_bf16_f32 v82, v82, v83
	v_cvt_pk_bf16_f32 v83, v86, v87
	v_cvt_pk_bf16_f32 v84, v84, v85
	v_cvt_pk_bf16_f32 v85, v88, v89
	global_store_dwordx4 v[116:117], v[82:85], off offset:256 nt
	s_nop 1
	v_add_u32_e32 v82, s0, v221
	ds_read_b128 v[82:85], v82
	s_waitcnt lgkmcnt(0)
	v_mov_b32_e32 v86, v83
	v_mov_b32_e32 v87, v84
	v_mov_b32_e32 v83, v85
	v_pk_add_f32 v[82:83], v[86:87], v[82:83]
	s_nop 0
	v_add_f32_e32 v82, v82, v83
	v_rcp_f32_e32 v86, v82
	v_add_u32_e32 v82, s2, v220
	v_ashrrev_i32_e32 v83, 31, v82
	v_lshlrev_b64 v[82:83], 11, v[82:83]
	v_lshl_add_u64 v[82:83], s[18:19], 0, v[82:83]
	v_lshl_add_u64 v[88:89], v[82:83], 0, v[16:17]
	v_pk_mul_f32 v[84:85], v[98:99], v[86:87] op_sel_hi:[1,0]
	v_pk_mul_f32 v[82:83], v[96:97], v[86:87] op_sel_hi:[1,0]
	v_pk_mul_f32 v[90:91], v[104:105], v[86:87] op_sel_hi:[1,0]
	v_pk_mul_f32 v[92:93], v[102:103], v[86:87] op_sel_hi:[1,0]
	v_cvt_pk_bf16_f32 v82, v82, v83
	v_cvt_pk_bf16_f32 v83, v84, v85
	v_cvt_pk_bf16_f32 v84, v92, v93
	v_cvt_pk_bf16_f32 v85, v90, v91
	global_store_dwordx4 v[88:89], v[82:85], off nt
	v_pk_mul_f32 v[90:91], v[112:113], v[86:87] op_sel_hi:[1,0]
	s_nop 0
	v_pk_mul_f32 v[84:85], v[108:109], v[86:87] op_sel_hi:[1,0]
	v_pk_mul_f32 v[82:83], v[106:107], v[86:87] op_sel_hi:[1,0]
	v_pk_mul_f32 v[86:87], v[110:111], v[86:87] op_sel_hi:[1,0]
	v_cvt_pk_bf16_f32 v82, v82, v83
	v_cvt_pk_bf16_f32 v83, v84, v85
	v_cvt_pk_bf16_f32 v84, v86, v87
	v_cvt_pk_bf16_f32 v85, v90, v91
	global_store_dwordx4 v[88:89], v[82:85], off offset:256 nt
	s_nop 1
	v_add_u32_e32 v82, s0, v223
	ds_read_b128 v[82:85], v82
	s_waitcnt lgkmcnt(0)
	v_mov_b32_e32 v86, v83
	v_mov_b32_e32 v87, v84
	v_mov_b32_e32 v83, v85
	v_pk_add_f32 v[82:83], v[86:87], v[82:83]
	v_add_u32_e32 v84, s2, v222
	v_add_f32_e32 v82, v82, v83
	v_rcp_f32_e32 v82, v82
	v_ashrrev_i32_e32 v85, 31, v84
	v_lshlrev_b64 v[84:85], 11, v[84:85]
	v_lshl_add_u64 v[84:85], s[18:19], 0, v[84:85]
	v_pk_mul_f32 v[56:57], v[56:57], v[82:83] op_sel_hi:[1,0]
	v_pk_mul_f32 v[50:51], v[50:51], v[82:83] op_sel_hi:[1,0]
	v_pk_mul_f32 v[62:63], v[62:63], v[82:83] op_sel_hi:[1,0]
	v_pk_mul_f32 v[86:87], v[54:55], v[82:83] op_sel_hi:[1,0]
	v_lshl_add_u64 v[84:85], v[84:85], 0, v[16:17]
	v_cvt_pk_bf16_f32 v54, v50, v51
	v_cvt_pk_bf16_f32 v55, v56, v57
	v_cvt_pk_bf16_f32 v56, v86, v87
	v_cvt_pk_bf16_f32 v57, v62, v63
	global_store_dwordx4 v[84:85], v[54:57], off nt
	v_pk_mul_f32 v[50:51], v[52:53], v[82:83] op_sel_hi:[1,0]
	v_pk_mul_f32 v[52:53], v[60:61], v[82:83] op_sel_hi:[1,0]
	v_pk_mul_f32 v[54:55], v[58:59], v[82:83] op_sel_hi:[1,0]
	v_pk_mul_f32 v[56:57], v[68:69], v[82:83] op_sel_hi:[1,0]
	v_cvt_pk_bf16_f32 v50, v50, v51
	v_cvt_pk_bf16_f32 v51, v54, v55
	v_cvt_pk_bf16_f32 v52, v52, v53
	v_cvt_pk_bf16_f32 v53, v56, v57
	global_store_dwordx4 v[84:85], v[50:53], off offset:256 nt
	s_nop 1
	v_add_u32_e32 v50, s0, v225
	ds_read_b128 v[50:53], v50
	s_waitcnt lgkmcnt(0)
	v_mov_b32_e32 v54, v51
	v_mov_b32_e32 v55, v52
	v_mov_b32_e32 v51, v53
	v_pk_add_f32 v[50:51], v[54:55], v[50:51]
	s_nop 0
	v_add_f32_e32 v50, v50, v51
	v_rcp_f32_e32 v54, v50
	v_add_u32_e32 v50, s2, v224
	v_ashrrev_i32_e32 v51, 31, v50
	v_lshlrev_b64 v[50:51], 11, v[50:51]
	v_lshl_add_u64 v[50:51], s[18:19], 0, v[50:51]
	v_lshl_add_u64 v[56:57], v[50:51], 0, v[16:17]
	v_pk_mul_f32 v[52:53], v[66:67], v[54:55] op_sel_hi:[1,0]
	v_pk_mul_f32 v[50:51], v[64:65], v[54:55] op_sel_hi:[1,0]
	v_pk_mul_f32 v[58:59], v[72:73], v[54:55] op_sel_hi:[1,0]
	v_pk_mul_f32 v[60:61], v[70:71], v[54:55] op_sel_hi:[1,0]
	v_cvt_pk_bf16_f32 v50, v50, v51
	v_cvt_pk_bf16_f32 v51, v52, v53
	v_cvt_pk_bf16_f32 v52, v60, v61
	v_cvt_pk_bf16_f32 v53, v58, v59
	global_store_dwordx4 v[56:57], v[50:53], off nt
	v_pk_mul_f32 v[58:59], v[80:81], v[54:55] op_sel_hi:[1,0]
	s_nop 0
	v_pk_mul_f32 v[52:53], v[76:77], v[54:55] op_sel_hi:[1,0]
	v_pk_mul_f32 v[50:51], v[74:75], v[54:55] op_sel_hi:[1,0]
	v_pk_mul_f32 v[54:55], v[78:79], v[54:55] op_sel_hi:[1,0]
	v_cvt_pk_bf16_f32 v50, v50, v51
	v_cvt_pk_bf16_f32 v51, v52, v53
	v_cvt_pk_bf16_f32 v52, v54, v55
	v_cvt_pk_bf16_f32 v53, v58, v59
	global_store_dwordx4 v[56:57], v[50:53], off offset:256 nt
	s_nop 1
	v_add_u32_e32 v50, s0, v235
	ds_read_b128 v[50:53], v50
	s_waitcnt lgkmcnt(0)
	v_mov_b32_e32 v54, v51
	v_mov_b32_e32 v55, v52
	v_mov_b32_e32 v51, v53
	v_pk_add_f32 v[50:51], v[54:55], v[50:51]
	v_add_u32_e32 v52, s2, v234
	v_add_f32_e32 v50, v50, v51
	v_rcp_f32_e32 v50, v50
	v_ashrrev_i32_e32 v53, 31, v52
	v_lshlrev_b64 v[52:53], 11, v[52:53]
	v_lshl_add_u64 v[52:53], s[18:19], 0, v[52:53]
	v_pk_mul_f32 v[24:25], v[24:25], v[50:51] op_sel_hi:[1,0]
	v_pk_mul_f32 v[18:19], v[18:19], v[50:51] op_sel_hi:[1,0]
	v_pk_mul_f32 v[30:31], v[30:31], v[50:51] op_sel_hi:[1,0]
	v_pk_mul_f32 v[54:55], v[22:23], v[50:51] op_sel_hi:[1,0]
	v_lshl_add_u64 v[52:53], v[52:53], 0, v[16:17]
	v_cvt_pk_bf16_f32 v22, v18, v19
	v_cvt_pk_bf16_f32 v23, v24, v25
	v_cvt_pk_bf16_f32 v24, v54, v55
	v_cvt_pk_bf16_f32 v25, v30, v31
	global_store_dwordx4 v[52:53], v[22:25], off nt
	v_pk_mul_f32 v[18:19], v[20:21], v[50:51] op_sel_hi:[1,0]
	v_pk_mul_f32 v[20:21], v[28:29], v[50:51] op_sel_hi:[1,0]
	v_pk_mul_f32 v[22:23], v[26:27], v[50:51] op_sel_hi:[1,0]
	v_pk_mul_f32 v[24:25], v[36:37], v[50:51] op_sel_hi:[1,0]
	v_cvt_pk_bf16_f32 v18, v18, v19
	v_cvt_pk_bf16_f32 v19, v22, v23
	v_cvt_pk_bf16_f32 v20, v20, v21
	v_cvt_pk_bf16_f32 v21, v24, v25
	global_store_dwordx4 v[52:53], v[18:21], off offset:256 nt
	s_nop 1
	v_add_u32_e32 v18, s0, v237
	ds_read_b128 v[18:21], v18
	s_waitcnt lgkmcnt(0)
	v_mov_b32_e32 v22, v19
	v_mov_b32_e32 v23, v20
	v_mov_b32_e32 v19, v21
	v_pk_add_f32 v[18:19], v[22:23], v[18:19]
	s_nop 0
	v_add_f32_e32 v18, v18, v19
	v_rcp_f32_e32 v22, v18
	v_add_u32_e32 v18, s2, v236
	v_ashrrev_i32_e32 v19, 31, v18
	v_lshlrev_b64 v[18:19], 11, v[18:19]
	v_lshl_add_u64 v[18:19], s[18:19], 0, v[18:19]
	v_lshl_add_u64 v[24:25], v[18:19], 0, v[16:17]
	v_pk_mul_f32 v[20:21], v[34:35], v[22:23] op_sel_hi:[1,0]
	v_pk_mul_f32 v[18:19], v[32:33], v[22:23] op_sel_hi:[1,0]
	v_pk_mul_f32 v[26:27], v[40:41], v[22:23] op_sel_hi:[1,0]
	v_pk_mul_f32 v[28:29], v[38:39], v[22:23] op_sel_hi:[1,0]
	v_cvt_pk_bf16_f32 v18, v18, v19
	v_cvt_pk_bf16_f32 v19, v20, v21
	v_cvt_pk_bf16_f32 v20, v28, v29
	v_cvt_pk_bf16_f32 v21, v26, v27
	global_store_dwordx4 v[24:25], v[18:21], off nt
	v_pk_mul_f32 v[26:27], v[48:49], v[22:23] op_sel_hi:[1,0]
	s_nop 0
	v_pk_mul_f32 v[20:21], v[44:45], v[22:23] op_sel_hi:[1,0]
	v_pk_mul_f32 v[18:19], v[42:43], v[22:23] op_sel_hi:[1,0]
	v_pk_mul_f32 v[22:23], v[46:47], v[22:23] op_sel_hi:[1,0]
	v_cvt_pk_bf16_f32 v18, v18, v19
	v_cvt_pk_bf16_f32 v19, v20, v21
	v_cvt_pk_bf16_f32 v20, v22, v23
	v_cvt_pk_bf16_f32 v21, v26, v27
	global_store_dwordx4 v[24:25], v[18:21], off offset:256 nt
	s_nop 1
	v_add_u32_e32 v18, s0, v239
	ds_read_b128 v[18:21], v18
	s_mov_b64 s[0:1], -1
	s_waitcnt lgkmcnt(0)
	v_mov_b32_e32 v22, v19
	v_mov_b32_e32 v23, v20
	v_mov_b32_e32 v19, v21
	v_pk_add_f32 v[18:19], v[22:23], v[18:19]
	v_add_u32_e32 v20, s2, v238
	v_add_f32_e32 v18, v18, v19
	v_rcp_f32_e32 v18, v18
	v_ashrrev_i32_e32 v21, 31, v20
	v_lshlrev_b64 v[20:21], 11, v[20:21]
	v_lshl_add_u64 v[20:21], s[18:19], 0, v[20:21]
	v_lshl_add_u64 v[16:17], v[20:21], 0, v[16:17]
	v_pk_mul_f32 v[6:7], v[6:7], v[18:19] op_sel_hi:[1,0]
	v_pk_mul_f32 v[0:1], v[0:1], v[18:19] op_sel_hi:[1,0]
	v_pk_mul_f32 v[12:13], v[12:13], v[18:19] op_sel_hi:[1,0]
	v_pk_mul_f32 v[20:21], v[4:5], v[18:19] op_sel_hi:[1,0]
	v_cvt_pk_bf16_f32 v4, v0, v1
	v_cvt_pk_bf16_f32 v5, v6, v7
	v_cvt_pk_bf16_f32 v6, v20, v21
	v_cvt_pk_bf16_f32 v7, v12, v13
	global_store_dwordx4 v[16:17], v[4:7], off nt
	v_pk_mul_f32 v[0:1], v[2:3], v[18:19] op_sel_hi:[1,0]
	v_pk_mul_f32 v[2:3], v[10:11], v[18:19] op_sel_hi:[1,0]
	v_pk_mul_f32 v[4:5], v[8:9], v[18:19] op_sel_hi:[1,0]
	v_pk_mul_f32 v[6:7], v[14:15], v[18:19] op_sel_hi:[1,0]
	v_cvt_pk_bf16_f32 v0, v0, v1
	v_cvt_pk_bf16_f32 v1, v4, v5
	v_cvt_pk_bf16_f32 v2, v2, v3
	v_cvt_pk_bf16_f32 v3, v6, v7
	global_store_dwordx4 v[16:17], v[0:3], off offset:256 nt
	s_cbranch_vccnz .LBB0_1682
	v_readlane_b32 s0, v255, 31
	v_readlane_b32 s1, v255, 32
	s_andn2_b64 vcc, exec, s[0:1]
	s_cbranch_vccnz .LBB0_1681
	s_barrier
	s_branch .LBB0_1681
